# attention loop: loop-counter increments and next-tile address preamble hoisted into the VALU-idle PV MFMA gaps of the second key block, so only the barrier and three rare-path tests remain between the
# baseline (speedup 1.0000x reference)
; #define LAS __attribute__((address_space(3)))
; #define ATT_WAIT_V(n) asm volatile("s_waitcnt vmcnt(" #n ")" ::: "memory")
; #define ATT_BAR() do { asm volatile("s_waitcnt lgkmcnt(0)" ::: "memory"); __builtin_amdgcn_s_barrier(); asm volatile("" ::: "memory"); } while (0)
; #define ATT_KLD(tt, blk, KN) do { \
;         int _sw = ((l32 >> 1) & 7) << 4; asm volatile("" : "+v"(_sw)); const int _xo = _sw ^ (hi << 4); \
;         LAS const unsigned char* _kb = lds + ((tt) & 3) * SLOT + mp * 8192 + (blk) * 4096 + l32 * 128; \
;         _Pragma("unroll") for (int d0 = 0; d0 < 4; ++d0) KN[d0] = *(const LAS bf16x8*)(_kb + (_xo ^ (d0 << 5))); } while (0)
; #define ATT_VLD(DST, c) do { _Pragma("unroll") for (int d = 0; d < 4; ++d) DST[d] = *(const LAS bf16x8*)(_vb + d * 4096 + (_xv ^ ((c) << 4))); } while (0)
; __device__ __forceinline__ void attn_unit(const Args& a, LAS unsigned char* lds, float lam, int bh, int qb) {
;     ...
;     for (int t = 0; t < NT; ++t) {
;         if (t + 3 <= NT) ATT_WAIT_V(4); else ATT_WAIT_V(0);
;         ATT_BAR();
;         if (t + 3 < NT) ATT_ISSUE(t + 3, (t + 3) & 3);
;         if (t <= cq) {
;             const bool near = (t >= cq - 2);
;             int _swv = ((l32 >> 1) & 7) << 4; asm volatile("" : "+v"(_swv)); const int _xv = _swv ^ (hi << 4);
;             LAS const unsigned char* _vb = lds + (t & 3) * SLOT + 16384 + l32 * 128;
;             int relb = 64 * t - qrow + 191 + 4 * hi; asm volatile("" : "+v"(relb));
;             LAS const float* tp = tab + relb;
;             bf16x8 va[4], vc[4]; unsigned pk[8];
;             const float ref = 0.f;
;             bf16x8 kn[4];
;             ATT_VLD(va, 0); ATT_VLD(vc, 2); ATT_KLD(t, 1, kn);
.LBB0_519:
	v_exp_f32_e32 v82, v82
	v_exp_f32_e32 v83, v83
	v_exp_f32_e32 v84, v84
	v_exp_f32_e32 v85, v85
	v_add_f32_e32 v146, v161, v82
	v_add_f32_e32 v147, v161, v83
	v_add_f32_e32 v148, v161, v84
	v_add_f32_e32 v149, v161, v85
	v_cvt_pk_bf16_f32 v82, v82, v83
	v_cvt_pk_bf16_f32 v83, v84, v85
	v_exp_f32_e32 v84, v86
	v_exp_f32_e32 v85, v87
	v_exp_f32_e32 v86, v88
	v_exp_f32_e32 v87, v89
	v_add_f32_e32 v88, v146, v84
	v_add_f32_e32 v89, v147, v85
	v_add_f32_e32 v146, v148, v86
	v_add_f32_e32 v147, v149, v87
	v_cvt_pk_bf16_f32 v84, v84, v85
	v_cvt_pk_bf16_f32 v85, v86, v87
	v_exp_f32_e32 v86, v90
	v_exp_f32_e32 v87, v91
	v_exp_f32_e32 v90, v92
	v_exp_f32_e32 v91, v93
	v_add_f32_e32 v88, v88, v86
	v_add_f32_e32 v89, v89, v87
	v_add_f32_e32 v92, v146, v90
	v_add_f32_e32 v93, v147, v91
	v_cvt_pk_bf16_f32 v86, v86, v87
	v_cvt_pk_bf16_f32 v87, v90, v91
	v_exp_f32_e32 v90, v94
	v_exp_f32_e32 v91, v95
	v_exp_f32_e32 v94, v96
	v_exp_f32_e32 v95, v97
	v_add_f32_e32 v96, v88, v90
	v_add_f32_e32 v97, v89, v91
	v_cvt_pk_bf16_f32 v88, v90, v91
	v_add_f32_e32 v90, v96, v97
	s_max_u32 s2, s69, 1
	v_add_f32_e32 v92, v92, v94
	v_add_f32_e32 v93, v93, v95
	v_cvt_pk_bf16_f32 v89, v94, v95
	v_add_f32_e32 v91, v92, v93
	s_nop 0
	v_add_f32_e32 v90, v90, v91
	s_nop 0
	v_add_f32_e32 v228, v208, v90
	v_mfma_f32_32x32x16_bf16 v[18:33], v[82:85], v[142:145], v[18:33]
	v_mfma_f32_32x32x16_bf16 v[34:49], v[82:85], v[138:141], v[34:49]
	v_mfma_f32_32x32x16_bf16 v[50:65], v[82:85], v[134:137], v[50:65]
	v_mfma_f32_32x32x16_bf16 v[2:17], v[82:85], v[130:133], v[2:17]
	v_mfma_f32_32x32x16_bf16 v[18:33], v[86:89], v[126:129], v[18:33]
	v_mfma_f32_32x32x16_bf16 v[34:49], v[86:89], v[122:125], v[34:49]
	v_mfma_f32_32x32x16_bf16 v[50:65], v[86:89], v[118:121], v[50:65]
	v_mfma_f32_32x32x16_bf16 v[2:17], v[86:89], v[114:117], v[2:17]
	s_cmp_eq_u32 s2, 1
	s_cbranch_scc1 .LBB0_543
	v_lshl_add_u32 v82, s73, 7, v221
	s_lshl_b32 s73, s73, 1
	s_add_i32 s72, s70, -2
	v_subrev_u32_e32 v227, s66, v82
	s_addk_i32 s73, 0xff01
	s_mov_b32 s74, 4
	s_movk_i32 s14, 0x100
	s_mov_b32 s75, 0x10000
	v_mov_b64_e32 v[206:207], v[204:205]
	v_xor_b32_e32 v229, v212, v213
	v_sub_f32_e32 v208, 0, v226
	v_cmp_neq_f32_e32 vcc, 0, v226
	s_nop 1
	s_cmp_lg_u64 vcc, 0
	s_cselect_b32 s98, 1, 0
	s_mov_b32 s9, 1
	s_mov_b32 s8, 1
	s_cmp_ge_i32 s9, s72
	s_cselect_b64 s[2:3], -1, 0
	v_add_u32_e32 v239, 0x8000, v214
	v_xad_u32 v236, v229, 64, v239
	v_xad_u32 v237, v229, s42, v239
	v_add_u32_e32 v251, 0x10000, v169
	v_xad_u32 v242, v212, v213, v251
	v_xad_u32 v243, v212, v217, v251
	v_xad_u32 v244, v212, v218, v251
	v_xad_u32 v245, v212, v219, v251
	s_add_i32 s76, s68, 0x8000
	v_add_u32_e32 v240, 0x8000, v214
	v_add_u32_e32 v241, s76, v214
	v_xad_u32 v232, v212, v213, v241
	v_xad_u32 v233, v212, v217, v241
	v_xad_u32 v234, v212, v218, v241
	v_xad_u32 v235, v212, v219, v241
	v_add_u32_e32 v246, v240, v229
	v_xad_u32 v241, v229, 32, v240
	ds_read_b128 v[252:255], v232 offset:4096
	ds_read_b128 v[150:153], v233 offset:4096
	ds_read_b128 v[154:157], v234 offset:4096
	ds_read_b128 v[146:149], v235 offset:4096
	ds_read_b128 v[142:145], v246 offset:16384
	ds_read_b128 v[138:141], v246 offset:20480
	ds_read_b128 v[134:137], v246 offset:24576
	ds_read_b128 v[126:129], v246 offset:28672
	ds_read_b128 v[130:133], v241 offset:16384
	ds_read_b128 v[122:125], v241 offset:20480
	ds_read_b128 v[118:121], v241 offset:24576
	ds_read_b128 v[114:117], v241 offset:28672
	s_branch .LBB0_523

; #define LAS __attribute__((address_space(3)))
; #define ATT_WAIT_V(n) asm volatile("s_waitcnt vmcnt(" #n ")" ::: "memory")
; #define ATT_BAR() do { asm volatile("s_waitcnt lgkmcnt(0)" ::: "memory"); __builtin_amdgcn_s_barrier(); asm volatile("" ::: "memory"); } while (0)
; __device__ __forceinline__ void attn_unit(const Args& a, LAS unsigned char* lds, float lam, int bh, int qb) {
;     ...
;     for (int t = 0; t < NT; ++t) {
;         if (t + 3 <= NT) ATT_WAIT_V(4); else ATT_WAIT_V(0);
;         ATT_BAR();
;         if (t + 3 < NT) ATT_ISSUE(t + 3, (t + 3) & 3);
;         if (t <= cq) {
;             const bool near = (t >= cq - 2);
;             int _swv = ((l32 >> 1) & 7) << 4; asm volatile("" : "+v"(_swv)); const int _xv = _swv ^ (hi << 4);
;             LAS const unsigned char* _vb = lds + (t & 3) * SLOT + 16384 + l32 * 128;
;             int relb = 64 * t - qrow + 191 + 4 * hi; asm volatile("" : "+v"(relb));
;             LAS const float* tp = tab + relb;
.Latt_vm_done:
	s_waitcnt lgkmcnt(12)
	s_barrier
	s_cmp_gt_u32 s9, s70
	s_cbranch_scc1 .LBB0_522
	s_cmp_lg_u64 s[2:3], 0
	s_cbranch_scc1 .Latt_near_a

; #define ATT_KLD(tt, blk, KN) do { \
;         int _sw = ((l32 >> 1) & 7) << 4; asm volatile("" : "+v"(_sw)); const int _xo = _sw ^ (hi << 4); \
;         LAS const unsigned char* _kb = lds + ((tt) & 3) * SLOT + mp * 8192 + (blk) * 4096 + l32 * 128; \
;         _Pragma("unroll") for (int d0 = 0; d0 < 4; ++d0) KN[d0] = *(const LAS bf16x8*)(_kb + (_xo ^ (d0 << 5))); } while (0)
; #define ATT_SMM(KN, S) do { S = MFMA32(KN[0], qf[0], ((f32x16){})); _Pragma("unroll") for (int d0 = 1; d0 < 4; ++d0) S = MFMA32(KN[d0], qf[d0], S); } while (0)
; #define ATT_VLD(DST, c) do { _Pragma("unroll") for (int d = 0; d < 4; ++d) DST[d] = *(const LAS bf16x8*)(_vb + d * 4096 + (_xv ^ ((c) << 4))); } while (0)
; #define ATT_PV1(PK, jj, VF) do { const bf16x8 _P = __builtin_bit_cast(bf16x8, (u32x4){PK[4 * (jj)], PK[4 * (jj) + 1], PK[4 * (jj) + 2], PK[4 * (jj) + 3]}); \
;         _Pragma("unroll") for (int d = 0; d < 4; ++d) o[d] = MFMA32(_P, VF[d], o[d]); } while (0)
; #define ATT_FENCE() __builtin_amdgcn_sched_barrier(0)
; #define SCHED_A() do { _Pragma("unroll") for (int _i = 0; _i < 4; ++_i) { __builtin_amdgcn_sched_group_barrier(0x008, 1, 0); __builtin_amdgcn_sched_group_barrier(0x002, 12, 0); } } while (0)
; #define SCHED_A() do {} while (0)
; __device__ __forceinline__ void attn_unit(const Args& a, LAS unsigned char* lds, float lam, int bh, int qb) {
;     ...
;             ATT_VLD(va, 0); ATT_VLD(vc, 2); ATT_KLD(t, 1, kn);
;             const float nsX = sm_pre(sX, near, tp, ref, t == 0, (t & 3) == 0, mhat, lsum, o, wsf, l32, hi);
;             ATT_FENCE();
;             ATT_SMM(kn, sY);
;             sm_exp(sX, nsX, lsum, pk);
;             SCHED_A();
;             ATT_FENCE();
;             ATT_PV1(pk, 0, va); ATT_PV1(pk, 1, vc);
;             ATT_FENCE();
;             ATT_VLD(va, 4); ATT_VLD(vc, 6); ATT_KLD(t + 1, 0, kn);
.Latt_fast_a:
	s_waitcnt lgkmcnt(8)
	v_mfma_f32_32x32x16_bf16 v[82:97], v[252:255], v[98:101], 0
	v_exp_f32_e32 v66, v66
	v_exp_f32_e32 v67, v67
	v_exp_f32_e32 v68, v68
	v_mfma_f32_32x32x16_bf16 v[82:97], v[150:153], v[102:105], v[82:97]
	v_exp_f32_e32 v69, v69
	v_exp_f32_e32 v70, v70
	v_exp_f32_e32 v71, v71
	v_mfma_f32_32x32x16_bf16 v[82:97], v[154:157], v[106:109], v[82:97]
	v_exp_f32_e32 v72, v72
	v_exp_f32_e32 v73, v73
	v_add_f32_e32 v247, v66, v70
	v_add_f32_e32 v248, v67, v71
	v_mfma_f32_32x32x16_bf16 v[82:97], v[146:149], v[110:113], v[82:97]
	v_add_f32_e32 v249, v68, v72
	v_add_f32_e32 v250, v69, v73
	v_cvt_pk_bf16_f32 v66, v66, v67
	v_cvt_pk_bf16_f32 v67, v68, v69
	v_cvt_pk_bf16_f32 v68, v70, v71
	v_cvt_pk_bf16_f32 v69, v72, v73
	v_exp_f32_e32 v74, v74
	s_waitcnt lgkmcnt(0)
	v_mfma_f32_32x32x16_bf16 v[18:33], v[66:69], v[142:145], v[18:33]
	v_exp_f32_e32 v75, v75
	v_exp_f32_e32 v76, v76
	v_exp_f32_e32 v77, v77
	ds_read_b128 v[252:255], v242
	ds_read_b128 v[150:153], v243
	v_mfma_f32_32x32x16_bf16 v[34:49], v[66:69], v[138:141], v[34:49]
	v_add_f32_e32 v247, v247, v74
	v_add_f32_e32 v248, v248, v75
	v_add_f32_e32 v249, v249, v76
	v_add_f32_e32 v250, v250, v77
	v_cvt_pk_bf16_f32 v70, v74, v75
	v_cvt_pk_bf16_f32 v71, v76, v77
	ds_read_b128 v[154:157], v244
	ds_read_b128 v[146:149], v245
	ds_read_b128 v[142:145], v236 offset:16384
	v_mfma_f32_32x32x16_bf16 v[50:65], v[66:69], v[134:137], v[50:65]
	v_exp_f32_e32 v78, v78
	v_exp_f32_e32 v79, v79
	v_exp_f32_e32 v80, v80
	ds_read_b128 v[138:141], v236 offset:20480
	v_mfma_f32_32x32x16_bf16 v[2:17], v[66:69], v[126:129], v[2:17]
	v_exp_f32_e32 v81, v81
	v_add_f32_e32 v247, v247, v78
	v_add_f32_e32 v248, v248, v79
	v_add_f32_e32 v249, v249, v80
	v_add_f32_e32 v250, v250, v81
	v_cvt_pk_bf16_f32 v72, v78, v79
	v_cvt_pk_bf16_f32 v73, v80, v81
	ds_read_b128 v[134:137], v236 offset:24576
	s_add_i32 s76, s75, 0x10000
	s_and_b32 s76, s76, 0x18000
	s_add_i32 s76, s67, s76
	s_cmp_ge_u32 s74, s69
	s_cbranch_scc1 .Latt_tail_nodma
	v_mfma_f32_32x32x16_bf16 v[18:33], v[70:73], v[130:133], v[18:33]
	v_add_f32_e32 v247, v247, v248
	v_add_f32_e32 v249, v249, v250
	v_add_f32_e32 v247, v247, v249
	v_add_f32_e32 v228, v228, v247
	ds_read_b128 v[126:129], v237 offset:16384
	v_lshl_add_u64 v[232:233], v[206:207], 0, s[28:29]
	s_mov_b32 m0, s76
	v_lshl_add_u64 v[234:235], s[14:15], 1, v[174:175]
	global_load_lds_dwordx4 v[232:233], off
	v_mfma_f32_32x32x16_bf16 v[34:49], v[70:73], v[122:125], v[34:49]
	ds_read_b128 v[130:133], v236 offset:28672
	s_add_i32 m0, s76, 0x2000
	s_nop 0
	global_load_lds_dwordx4 v[206:207], off
	v_mfma_f32_32x32x16_bf16 v[50:65], v[70:73], v[118:121], v[50:65]
	ds_read_b128 v[122:125], v237 offset:20480
	s_add_i32 m0, s76, 0x4000
	s_nop 0
	global_load_lds_dwordx4 v[234:235], off
	v_lshl_add_u64 v[234:235], v[234:235], 0, s[18:19]
	v_mfma_f32_32x32x16_bf16 v[2:17], v[70:73], v[114:117], v[2:17]
	ds_read_b128 v[118:121], v237 offset:24576
	ds_read_b128 v[114:117], v237 offset:28672
	s_add_i32 m0, s76, 0x6000
	s_nop 0
	global_load_lds_dwordx4 v[234:235], off

; #define ATT_KLD(tt, blk, KN) do { \
;         int _sw = ((l32 >> 1) & 7) << 4; asm volatile("" : "+v"(_sw)); const int _xo = _sw ^ (hi << 4); \
;         LAS const unsigned char* _kb = lds + ((tt) & 3) * SLOT + mp * 8192 + (blk) * 4096 + l32 * 128; \
;         _Pragma("unroll") for (int d0 = 0; d0 < 4; ++d0) KN[d0] = *(const LAS bf16x8*)(_kb + (_xo ^ (d0 << 5))); } while (0)
; #define ATT_SMM(KN, S) do { S = MFMA32(KN[0], qf[0], ((f32x16){})); _Pragma("unroll") for (int d0 = 1; d0 < 4; ++d0) S = MFMA32(KN[d0], qf[d0], S); } while (0)
; #define ATT_VLD(DST, c) do { _Pragma("unroll") for (int d = 0; d < 4; ++d) DST[d] = *(const LAS bf16x8*)(_vb + d * 4096 + (_xv ^ ((c) << 4))); } while (0)
; #define ATT_PV1(PK, jj, VF) do { const bf16x8 _P = __builtin_bit_cast(bf16x8, (u32x4){PK[4 * (jj)], PK[4 * (jj) + 1], PK[4 * (jj) + 2], PK[4 * (jj) + 3]}); \
;         _Pragma("unroll") for (int d = 0; d < 4; ++d) o[d] = MFMA32(_P, VF[d], o[d]); } while (0)
; #define ATT_FENCE() __builtin_amdgcn_sched_barrier(0)
; #define SCHED_A() do { _Pragma("unroll") for (int _i = 0; _i < 4; ++_i) { __builtin_amdgcn_sched_group_barrier(0x008, 1, 0); __builtin_amdgcn_sched_group_barrier(0x002, 12, 0); } } while (0)
; #define SCHED_A() do {} while (0)
; __device__ __forceinline__ void attn_unit(const Args& a, LAS unsigned char* lds, float lam, int bh, int qb) {
;     ...
;             ATT_VLD(va, 4); ATT_VLD(vc, 6); ATT_KLD(t + 1, 0, kn);
;             const float nsY = sm_pre(sY, near, tp + 32, ref, false, false, mhat, lsum, o, wsf, l32, hi);
;             ATT_FENCE();
;             ATT_SMM(kn, sX);
;             sm_exp(sY, nsY, lsum, pk);
;             SCHED_A();
;             ATT_FENCE();
;             ATT_PV1(pk, 0, va); ATT_PV1(pk, 1, vc);
;             ATT_FENCE();
.Latt_fast_b:
	s_add_i32 s76, s74, -2
	s_and_b32 s76, s76, 3
	s_lshl_b32 s76, s76, 15
	v_add_u32_e32 v240, s76, v214
	s_add_i32 s76, s76, s68
	v_add_u32_e32 v241, s76, v214
	v_xad_u32 v242, v212, v213, v241
	v_xad_u32 v243, v212, v217, v241
	v_xad_u32 v244, v212, v218, v241
	v_xad_u32 v245, v212, v219, v241
	v_add_u32_e32 v246, v240, v229
	v_xad_u32 v241, v229, 32, v240
	s_waitcnt lgkmcnt(8)
	v_mfma_f32_32x32x16_bf16 v[66:81], v[252:255], v[98:101], 0
	v_exp_f32_e32 v82, v82
	v_exp_f32_e32 v83, v83
	v_exp_f32_e32 v84, v84
	v_mfma_f32_32x32x16_bf16 v[66:81], v[150:153], v[102:105], v[66:81]
	v_exp_f32_e32 v85, v85
	v_exp_f32_e32 v86, v86
	v_exp_f32_e32 v87, v87
	ds_read_b128 v[252:255], v242 offset:4096
	v_mfma_f32_32x32x16_bf16 v[66:81], v[154:157], v[106:109], v[66:81]
	v_exp_f32_e32 v88, v88
	v_exp_f32_e32 v89, v89
	v_add_f32_e32 v247, v82, v86
	v_add_f32_e32 v248, v83, v87
	ds_read_b128 v[150:153], v243 offset:4096
	v_mfma_f32_32x32x16_bf16 v[66:81], v[146:149], v[110:113], v[66:81]
	v_add_f32_e32 v249, v84, v88
	v_add_f32_e32 v250, v85, v89
	v_cvt_pk_bf16_f32 v82, v82, v83
	v_cvt_pk_bf16_f32 v83, v84, v85
	v_cvt_pk_bf16_f32 v84, v86, v87
	v_cvt_pk_bf16_f32 v85, v88, v89
	v_exp_f32_e32 v90, v90
	ds_read_b128 v[154:157], v244 offset:4096
	s_waitcnt lgkmcnt(3)
	v_mfma_f32_32x32x16_bf16 v[18:33], v[82:85], v[142:145], v[18:33]
	v_exp_f32_e32 v91, v91
	v_exp_f32_e32 v92, v92
	v_exp_f32_e32 v93, v93
	ds_read_b128 v[146:149], v245 offset:4096
	v_mfma_f32_32x32x16_bf16 v[34:49], v[82:85], v[138:141], v[34:49]
	v_add_f32_e32 v247, v247, v90
	v_add_f32_e32 v248, v248, v91
	v_add_f32_e32 v249, v249, v92
	v_add_f32_e32 v250, v250, v93
	v_cvt_pk_bf16_f32 v86, v90, v91
	v_cvt_pk_bf16_f32 v87, v92, v93
	ds_read_b128 v[142:145], v246 offset:16384
	v_mfma_f32_32x32x16_bf16 v[50:65], v[82:85], v[134:137], v[50:65]
	v_exp_f32_e32 v94, v94
	v_exp_f32_e32 v95, v95
	v_exp_f32_e32 v96, v96
	ds_read_b128 v[138:141], v246 offset:20480
	v_mfma_f32_32x32x16_bf16 v[2:17], v[82:85], v[130:133], v[2:17]
	v_exp_f32_e32 v97, v97
	v_add_f32_e32 v247, v247, v94
	v_add_f32_e32 v248, v248, v95
	v_add_f32_e32 v249, v249, v96
	v_add_f32_e32 v250, v250, v97
	v_cvt_pk_bf16_f32 v88, v94, v95
	v_cvt_pk_bf16_f32 v89, v96, v97
	ds_read_b128 v[134:137], v246 offset:24576
	s_nop 0
	v_mfma_f32_32x32x16_bf16 v[18:33], v[86:89], v[126:129], v[18:33]
	v_add_f32_e32 v247, v247, v248
	v_add_f32_e32 v249, v249, v250
	v_add_f32_e32 v247, v247, v249
	v_add_f32_e32 v228, v228, v247
	ds_read_b128 v[130:133], v241 offset:16384
	s_add_i32 s74, s74, 1
	s_add_i32 s14, s14, 64
	s_add_i32 s75, s75, 0x8000
	v_lshl_add_u64 v[206:207], v[206:207], 0, s[30:31]
	s_add_i32 s9, s74, -3
	s_and_b32 s8, s9, 3
	s_lshl_b32 s76, s8, 15
	v_add_u32_e32 v239, s76, v214
	v_mfma_f32_32x32x16_bf16 v[34:49], v[86:89], v[122:125], v[34:49]
	ds_read_b128 v[126:129], v246 offset:28672
	s_and_b32 s76, s75, 0x18000
	v_xad_u32 v236, v229, 64, v239
	v_xad_u32 v237, v229, s42, v239
	v_add_u32_e32 v251, s76, v169
	v_mfma_f32_32x32x16_bf16 v[50:65], v[86:89], v[118:121], v[50:65]
	ds_read_b128 v[122:125], v241 offset:20480
	v_xad_u32 v242, v212, v213, v251
	v_xad_u32 v243, v212, v217, v251
	v_xad_u32 v244, v212, v218, v251
	v_xad_u32 v245, v212, v219, v251
	v_mfma_f32_32x32x16_bf16 v[2:17], v[86:89], v[114:117], v[2:17]
	ds_read_b128 v[118:121], v241 offset:24576
	ds_read_b128 v[114:117], v241 offset:28672
	s_cmp_ge_i32 s9, s72
	s_cselect_b64 s[2:3], -1, 0
	s_add_i32 s99, s73, s74
	s_cmp_eq_u32 s99, 4
	s_cbranch_scc1 .LBB0_543
	s_branch .LBB0_523

; #define ATT_KLD(tt, blk, KN) do { \
;         int _sw = ((l32 >> 1) & 7) << 4; asm volatile("" : "+v"(_sw)); const int _xo = _sw ^ (hi << 4); \
;         LAS const unsigned char* _kb = lds + ((tt) & 3) * SLOT + mp * 8192 + (blk) * 4096 + l32 * 128; \
;         _Pragma("unroll") for (int d0 = 0; d0 < 4; ++d0) KN[d0] = *(const LAS bf16x8*)(_kb + (_xo ^ (d0 << 5))); } while (0)
; #define ATT_SMM(KN, S) do { S = MFMA32(KN[0], qf[0], ((f32x16){})); _Pragma("unroll") for (int d0 = 1; d0 < 4; ++d0) S = MFMA32(KN[d0], qf[d0], S); } while (0)
; #define ATT_VLD(DST, c) do { _Pragma("unroll") for (int d = 0; d < 4; ++d) DST[d] = *(const LAS bf16x8*)(_vb + d * 4096 + (_xv ^ ((c) << 4))); } while (0)
; #define ATT_PV1(PK, jj, VF) do { const bf16x8 _P = __builtin_bit_cast(bf16x8, (u32x4){PK[4 * (jj)], PK[4 * (jj) + 1], PK[4 * (jj) + 2], PK[4 * (jj) + 3]}); \
;         _Pragma("unroll") for (int d = 0; d < 4; ++d) o[d] = MFMA32(_P, VF[d], o[d]); } while (0)
; #define ATT_FENCE() __builtin_amdgcn_sched_barrier(0)
; #define SCHED_A() do { _Pragma("unroll") for (int _i = 0; _i < 4; ++_i) { __builtin_amdgcn_sched_group_barrier(0x008, 1, 0); __builtin_amdgcn_sched_group_barrier(0x002, 12, 0); } } while (0)
; #define SCHED_A() do {} while (0)
; __device__ __forceinline__ void attn_unit(const Args& a, LAS unsigned char* lds, float lam, int bh, int qb) {
;     ...
;             ATT_PV1(pk, 0, va); ATT_PV1(pk, 1, vc);
;             ATT_FENCE();
;             ATT_VLD(va, 4); ATT_VLD(vc, 6); ATT_KLD(t + 1, 0, kn);
;             const float nsY = sm_pre(sY, near, tp + 32, ref, false, false, mhat, lsum, o, wsf, l32, hi);
;             ATT_FENCE();
;             ATT_SMM(kn, sX);
;             sm_exp(sY, nsY, lsum, pk);
;             SCHED_A();
;             ATT_FENCE();
;             ATT_PV1(pk, 0, va); ATT_PV1(pk, 1, vc);
;             ATT_FENCE();
.Latt_tail_nodma:
	v_mfma_f32_32x32x16_bf16 v[18:33], v[70:73], v[130:133], v[18:33]
	v_add_f32_e32 v247, v247, v248
	v_add_f32_e32 v249, v249, v250
	v_add_f32_e32 v247, v247, v249
	v_add_f32_e32 v228, v228, v247
	ds_read_b128 v[126:129], v237 offset:16384
	v_mfma_f32_32x32x16_bf16 v[34:49], v[70:73], v[122:125], v[34:49]
	ds_read_b128 v[130:133], v236 offset:28672
	v_mfma_f32_32x32x16_bf16 v[50:65], v[70:73], v[118:121], v[50:65]
	ds_read_b128 v[122:125], v237 offset:20480
	v_mfma_f32_32x32x16_bf16 v[2:17], v[70:73], v[114:117], v[2:17]
	ds_read_b128 v[118:121], v237 offset:24576
	ds_read_b128 v[114:117], v237 offset:28672
	s_branch .Latt_half_b

; #define LAS __attribute__((address_space(3)))
; #define ATT_WAIT_V(n) asm volatile("s_waitcnt vmcnt(" #n ")" ::: "memory")
; #define ATT_BAR() do { asm volatile("s_waitcnt lgkmcnt(0)" ::: "memory"); __builtin_amdgcn_s_barrier(); asm volatile("" ::: "memory"); } while (0)
; __device__ __forceinline__ void attn_unit(const Args& a, LAS unsigned char* lds, float lam, int bh, int qb) {
;     ...
;     for (int t = 0; t < NT; ++t) {
;         if (t + 3 <= NT) ATT_WAIT_V(4); else ATT_WAIT_V(0);
;         ATT_BAR();
;         if (t + 3 < NT) ATT_ISSUE(t + 3, (t + 3) & 3);
;         if (t <= cq) {
;             const bool near = (t >= cq - 2);
;             int _swv = ((l32 >> 1) & 7) << 4; asm volatile("" : "+v"(_swv)); const int _xv = _swv ^ (hi << 4);
;             LAS const unsigned char* _vb = lds + (t & 3) * SLOT + 16384 + l32 * 128;
;             int relb = 64 * t - qrow + 191 + 4 * hi; asm volatile("" : "+v"(relb));
;             LAS const float* tp = tab + relb;
.LBB0_522:
	s_add_i32 s74, s74, 1
	s_add_i32 s14, s14, 64
	s_add_i32 s75, s75, 0x8000
	v_lshl_add_u64 v[206:207], v[206:207], 0, s[30:31]
	s_add_i32 s9, s74, -3
	s_and_b32 s8, s9, 3
	s_lshl_b32 s76, s8, 15
	v_add_u32_e32 v239, s76, v214
	s_and_b32 s76, s75, 0x18000
	v_xad_u32 v236, v229, 64, v239
	v_xad_u32 v237, v229, s42, v239
	v_add_u32_e32 v251, s76, v169
	v_xad_u32 v242, v212, v213, v251
	v_xad_u32 v243, v212, v217, v251
	v_xad_u32 v244, v212, v218, v251
	v_xad_u32 v245, v212, v219, v251
	s_cmp_ge_i32 s9, s72
	s_cselect_b64 s[2:3], -1, 0
	s_add_i32 s99, s73, s74
	s_cmp_eq_u32 s99, 4
	s_cbranch_scc1 .LBB0_543
	s_branch .LBB0_523
